# proj epilogue: 8 rstd loads hoisted, single wait
# speedup vs baseline: 1.0009x; 1.0009x over previous
.LBB0_252:
	v_lshl_add_u32 v146, s24, 8, v1
	v_ashrrev_i32_e32 v147, 31, v146
	v_lshl_add_u64 v[150:151], v[146:147], 2, s[10:11]
	global_load_dword v160, v[150:151], off
	global_load_dword v170, v[150:151], off offset:64
	global_load_dword v172, v[150:151], off offset:128
	global_load_dword v174, v[150:151], off offset:192
	global_load_dword v176, v[150:151], off offset:512
	global_load_dword v178, v[150:151], off offset:576
	global_load_dword v180, v[150:151], off offset:640
	global_load_dword v182, v[150:151], off offset:704
	v_lshl_or_b32 v152, s49, 8, v155
	v_mov_b64_e32 v[148:149], s[8:9]
	v_ashrrev_i32_e32 v153, 31, v152
	v_mad_i64_i32 v[162:163], s[26:27], v146, s48, v[148:149]
	v_or_b32_e32 v164, 16, v146
	v_lshlrev_b64 v[152:153], 1, v[152:153]
	v_ashrrev_i32_e32 v165, 31, v164
	v_lshl_add_u64 v[162:163], v[162:163], 0, v[152:153]
	v_lshl_add_u64 v[166:167], v[164:165], 2, s[10:11]
	s_andn2_b64 vcc, exec, s[4:5]
	s_mov_b64 s[4:5], -1
	s_waitcnt vmcnt(0)
	v_pk_mul_f32 v[128:129], v[128:129], v[160:161] op_sel_hi:[1,0]
	v_pk_mul_f32 v[126:127], v[126:127], v[160:161] op_sel_hi:[1,0]
	v_pk_mul_f32 v[124:125], v[124:125], v[160:161] op_sel_hi:[1,0]
	v_pk_mul_f32 v[122:123], v[122:123], v[160:161] op_sel_hi:[1,0]
	v_pk_mul_f32 v[120:121], v[120:121], v[160:161] op_sel_hi:[1,0]
	v_pk_mul_f32 v[118:119], v[118:119], v[160:161] op_sel_hi:[1,0]
	v_pk_mul_f32 v[168:169], v[116:117], v[160:161] op_sel_hi:[1,0]
	v_pk_mul_f32 v[160:161], v[114:115], v[160:161] op_sel_hi:[1,0]
	v_cvt_pk_bf16_f32 v114, v126, v127
	v_cvt_pk_bf16_f32 v115, v128, v129
	v_cvt_pk_bf16_f32 v116, v122, v123
	v_cvt_pk_bf16_f32 v117, v124, v125
	global_store_dwordx4 v[162:163], v[114:117], off
	s_nop 1
	v_cvt_pk_bf16_f32 v114, v118, v119
	v_cvt_pk_bf16_f32 v115, v120, v121
	v_cvt_pk_bf16_f32 v116, v160, v161
	v_cvt_pk_bf16_f32 v117, v168, v169
	global_store_dwordx4 v[162:163], v[114:117], off offset:256
	s_nop 1
	v_mov_b32_e32 v114, v170
	v_mad_i64_i32 v[118:119], s[26:27], v164, s48, v[148:149]
	v_or_b32_e32 v116, 32, v146
	v_ashrrev_i32_e32 v117, 31, v116
	v_lshl_add_u64 v[118:119], v[118:119], 0, v[152:153]
	v_lshl_add_u64 v[120:121], v[116:117], 2, s[10:11]
	v_pk_mul_f32 v[112:113], v[112:113], v[114:115] op_sel_hi:[1,0]
	v_pk_mul_f32 v[110:111], v[110:111], v[114:115] op_sel_hi:[1,0]
	v_pk_mul_f32 v[108:109], v[108:109], v[114:115] op_sel_hi:[1,0]
	v_pk_mul_f32 v[106:107], v[106:107], v[114:115] op_sel_hi:[1,0]
	v_pk_mul_f32 v[104:105], v[104:105], v[114:115] op_sel_hi:[1,0]
	v_pk_mul_f32 v[102:103], v[102:103], v[114:115] op_sel_hi:[1,0]
	v_pk_mul_f32 v[122:123], v[100:101], v[114:115] op_sel_hi:[1,0]
	v_pk_mul_f32 v[114:115], v[98:99], v[114:115] op_sel_hi:[1,0]
	v_cvt_pk_bf16_f32 v98, v110, v111
	v_cvt_pk_bf16_f32 v99, v112, v113
	v_cvt_pk_bf16_f32 v100, v106, v107
	v_cvt_pk_bf16_f32 v101, v108, v109
	global_store_dwordx4 v[118:119], v[98:101], off
	s_nop 1
	v_cvt_pk_bf16_f32 v98, v102, v103
	v_cvt_pk_bf16_f32 v99, v104, v105
	v_cvt_pk_bf16_f32 v100, v114, v115
	v_cvt_pk_bf16_f32 v101, v122, v123
	global_store_dwordx4 v[118:119], v[98:101], off offset:256
	s_nop 1
	v_mov_b32_e32 v98, v172
	v_mad_i64_i32 v[102:103], s[26:27], v116, s48, v[148:149]
	v_or_b32_e32 v100, 48, v146
	v_ashrrev_i32_e32 v101, 31, v100
	v_lshl_add_u64 v[102:103], v[102:103], 0, v[152:153]
	v_lshl_add_u64 v[104:105], v[100:101], 2, s[10:11]
	v_pk_mul_f32 v[96:97], v[96:97], v[98:99] op_sel_hi:[1,0]
	v_pk_mul_f32 v[94:95], v[94:95], v[98:99] op_sel_hi:[1,0]
	v_pk_mul_f32 v[92:93], v[92:93], v[98:99] op_sel_hi:[1,0]
	v_pk_mul_f32 v[90:91], v[90:91], v[98:99] op_sel_hi:[1,0]
	v_pk_mul_f32 v[84:85], v[84:85], v[98:99] op_sel_hi:[1,0]
	v_pk_mul_f32 v[82:83], v[82:83], v[98:99] op_sel_hi:[1,0]
	v_pk_mul_f32 v[106:107], v[76:77], v[98:99] op_sel_hi:[1,0]
	v_pk_mul_f32 v[98:99], v[74:75], v[98:99] op_sel_hi:[1,0]
	v_cvt_pk_bf16_f32 v74, v94, v95
	v_cvt_pk_bf16_f32 v75, v96, v97
	v_cvt_pk_bf16_f32 v76, v90, v91
	v_cvt_pk_bf16_f32 v77, v92, v93
	global_store_dwordx4 v[102:103], v[74:77], off
	s_nop 1
	v_cvt_pk_bf16_f32 v74, v82, v83
	v_cvt_pk_bf16_f32 v75, v84, v85
	v_cvt_pk_bf16_f32 v76, v98, v99
	v_cvt_pk_bf16_f32 v77, v106, v107
	global_store_dwordx4 v[102:103], v[74:77], off offset:256
	s_nop 1
	v_mov_b32_e32 v74, v174
	v_pk_mul_f32 v[82:83], v[88:89], v[74:75] op_sel_hi:[1,0]
	v_mad_i64_i32 v[76:77], s[26:27], v100, s48, v[148:149]
	v_lshl_add_u64 v[76:77], v[76:77], 0, v[152:153]
	v_pk_mul_f32 v[84:85], v[86:87], v[74:75] op_sel_hi:[1,0]
	v_pk_mul_f32 v[80:81], v[80:81], v[74:75] op_sel_hi:[1,0]
	v_pk_mul_f32 v[78:79], v[78:79], v[74:75] op_sel_hi:[1,0]
	v_pk_mul_f32 v[72:73], v[72:73], v[74:75] op_sel_hi:[1,0]
	v_pk_mul_f32 v[70:71], v[70:71], v[74:75] op_sel_hi:[1,0]
	v_pk_mul_f32 v[86:87], v[68:69], v[74:75] op_sel_hi:[1,0]
	v_pk_mul_f32 v[74:75], v[66:67], v[74:75] op_sel_hi:[1,0]
	v_cvt_pk_bf16_f32 v66, v84, v85
	v_cvt_pk_bf16_f32 v67, v82, v83
	v_cvt_pk_bf16_f32 v68, v78, v79
	v_cvt_pk_bf16_f32 v69, v80, v81
	global_store_dwordx4 v[76:77], v[66:69], off
	s_nop 1
	v_cvt_pk_bf16_f32 v66, v70, v71
	v_cvt_pk_bf16_f32 v67, v72, v73
	v_cvt_pk_bf16_f32 v68, v74, v75
	v_cvt_pk_bf16_f32 v69, v86, v87
	global_store_dwordx4 v[76:77], v[66:69], off offset:256
	s_nop 1
	v_mov_b32_e32 v66, v176
	s_nop 0
	v_add_u32_e32 v67, 0x80, v146
	v_mad_i64_i32 v[68:69], s[26:27], v67, s48, v[148:149]
	v_lshl_add_u64 v[68:69], v[68:69], 0, v[152:153]
	v_pk_mul_f32 v[64:65], v[64:65], v[66:67] op_sel_hi:[1,0]
	v_pk_mul_f32 v[62:63], v[62:63], v[66:67] op_sel_hi:[1,0]
	v_pk_mul_f32 v[60:61], v[60:61], v[66:67] op_sel_hi:[1,0]
	v_pk_mul_f32 v[58:59], v[58:59], v[66:67] op_sel_hi:[1,0]
	v_pk_mul_f32 v[56:57], v[56:57], v[66:67] op_sel_hi:[1,0]
	v_pk_mul_f32 v[54:55], v[54:55], v[66:67] op_sel_hi:[1,0]
	v_pk_mul_f32 v[70:71], v[52:53], v[66:67] op_sel_hi:[1,0]
	v_pk_mul_f32 v[66:67], v[50:51], v[66:67] op_sel_hi:[1,0]
	v_cvt_pk_bf16_f32 v50, v62, v63
	v_cvt_pk_bf16_f32 v51, v64, v65
	v_cvt_pk_bf16_f32 v52, v58, v59
	v_cvt_pk_bf16_f32 v53, v60, v61
	global_store_dwordx4 v[68:69], v[50:53], off
	s_nop 1
	v_cvt_pk_bf16_f32 v50, v54, v55
	v_cvt_pk_bf16_f32 v51, v56, v57
	v_cvt_pk_bf16_f32 v52, v66, v67
	v_cvt_pk_bf16_f32 v53, v70, v71
	global_store_dwordx4 v[68:69], v[50:53], off offset:256
	s_nop 1
	v_mov_b32_e32 v50, v178
	s_nop 0
	v_add_u32_e32 v51, 0x90, v146
	v_mad_i64_i32 v[52:53], s[26:27], v51, s48, v[148:149]
	v_lshl_add_u64 v[52:53], v[52:53], 0, v[152:153]
	v_pk_mul_f32 v[48:49], v[48:49], v[50:51] op_sel_hi:[1,0]
	v_pk_mul_f32 v[46:47], v[46:47], v[50:51] op_sel_hi:[1,0]
	v_pk_mul_f32 v[44:45], v[44:45], v[50:51] op_sel_hi:[1,0]
	v_pk_mul_f32 v[42:43], v[42:43], v[50:51] op_sel_hi:[1,0]
	v_pk_mul_f32 v[40:41], v[40:41], v[50:51] op_sel_hi:[1,0]
	v_pk_mul_f32 v[38:39], v[38:39], v[50:51] op_sel_hi:[1,0]
	v_pk_mul_f32 v[54:55], v[36:37], v[50:51] op_sel_hi:[1,0]
	v_pk_mul_f32 v[50:51], v[34:35], v[50:51] op_sel_hi:[1,0]
	v_cvt_pk_bf16_f32 v34, v46, v47
	v_cvt_pk_bf16_f32 v35, v48, v49
	v_cvt_pk_bf16_f32 v36, v42, v43
	v_cvt_pk_bf16_f32 v37, v44, v45
	global_store_dwordx4 v[52:53], v[34:37], off
	s_nop 1
	v_cvt_pk_bf16_f32 v34, v38, v39
	v_cvt_pk_bf16_f32 v35, v40, v41
	v_cvt_pk_bf16_f32 v36, v50, v51
	v_cvt_pk_bf16_f32 v37, v54, v55
	global_store_dwordx4 v[52:53], v[34:37], off offset:256
	s_nop 1
	v_mov_b32_e32 v34, v180
	s_nop 0
	v_add_u32_e32 v35, 0xa0, v146
	v_mad_i64_i32 v[36:37], s[26:27], v35, s48, v[148:149]
	v_lshl_add_u64 v[36:37], v[36:37], 0, v[152:153]
	v_pk_mul_f32 v[32:33], v[32:33], v[34:35] op_sel_hi:[1,0]
	v_pk_mul_f32 v[30:31], v[30:31], v[34:35] op_sel_hi:[1,0]
	v_pk_mul_f32 v[28:29], v[28:29], v[34:35] op_sel_hi:[1,0]
	v_pk_mul_f32 v[26:27], v[26:27], v[34:35] op_sel_hi:[1,0]
	v_pk_mul_f32 v[24:25], v[24:25], v[34:35] op_sel_hi:[1,0]
	v_pk_mul_f32 v[22:23], v[22:23], v[34:35] op_sel_hi:[1,0]
	v_pk_mul_f32 v[38:39], v[20:21], v[34:35] op_sel_hi:[1,0]
	v_pk_mul_f32 v[34:35], v[18:19], v[34:35] op_sel_hi:[1,0]
	v_cvt_pk_bf16_f32 v18, v30, v31
	v_cvt_pk_bf16_f32 v19, v32, v33
	v_cvt_pk_bf16_f32 v20, v26, v27
	v_cvt_pk_bf16_f32 v21, v28, v29
	global_store_dwordx4 v[36:37], v[18:21], off
	s_nop 1
	v_cvt_pk_bf16_f32 v18, v22, v23
	v_cvt_pk_bf16_f32 v19, v24, v25
	v_cvt_pk_bf16_f32 v20, v34, v35
	v_cvt_pk_bf16_f32 v21, v38, v39
	global_store_dwordx4 v[36:37], v[18:21], off offset:256
	s_nop 1
	v_mov_b32_e32 v18, v182
	s_nop 0
	v_add_u32_e32 v19, 0xb0, v146
	v_mad_i64_i32 v[20:21], s[26:27], v19, s48, v[148:149]
	v_lshl_add_u64 v[20:21], v[20:21], 0, v[152:153]
	v_pk_mul_f32 v[16:17], v[16:17], v[18:19] op_sel_hi:[1,0]
	v_pk_mul_f32 v[14:15], v[14:15], v[18:19] op_sel_hi:[1,0]
	v_pk_mul_f32 v[12:13], v[12:13], v[18:19] op_sel_hi:[1,0]
	v_pk_mul_f32 v[10:11], v[10:11], v[18:19] op_sel_hi:[1,0]
	v_pk_mul_f32 v[8:9], v[8:9], v[18:19] op_sel_hi:[1,0]
	v_pk_mul_f32 v[6:7], v[6:7], v[18:19] op_sel_hi:[1,0]
	v_pk_mul_f32 v[22:23], v[4:5], v[18:19] op_sel_hi:[1,0]
	v_pk_mul_f32 v[18:19], v[2:3], v[18:19] op_sel_hi:[1,0]
	v_cvt_pk_bf16_f32 v2, v14, v15
	v_cvt_pk_bf16_f32 v3, v16, v17
	v_cvt_pk_bf16_f32 v4, v10, v11
	v_cvt_pk_bf16_f32 v5, v12, v13
	global_store_dwordx4 v[20:21], v[2:5], off
	s_nop 1
	v_cvt_pk_bf16_f32 v2, v6, v7
	v_cvt_pk_bf16_f32 v3, v8, v9
	v_cvt_pk_bf16_f32 v4, v18, v19
	v_cvt_pk_bf16_f32 v5, v22, v23
	global_store_dwordx4 v[20:21], v[2:5], off offset:256
	s_cbranch_vccnz .LBB0_245
	s_andn2_b64 vcc, exec, s[6:7]
	s_cbranch_vccnz .LBB0_244
	s_barrier
	s_branch .LBB0_244
